# attention main loops: the pure-VALU head of the softmax join block (previous tile's row-sum adds, exps, bf16 packs) hoisted into the pipelined QK^T MFMA block (copy kept on the inactive-wave path); fr
# baseline (speedup 1.0000x reference)
.LBB0_1482:
	v_cndmask_b32_e64 v1, 0, 1, s[30:31]
	v_cmp_ne_u32_e64 s[4:5], 1, v1
	s_andn2_b64 vcc, exec, s[30:31]
	s_cbranch_vccnz .LBB0_1484
	ds_read_b128 v[100:103], v224
	ds_read_b128 v[104:107], v224 offset:32
	ds_read_b128 v[108:111], v224 offset:64
	s_waitcnt vmcnt(1)
	ds_read_b128 v[112:115], v224 offset:96
	ds_read_b128 v[84:87], v224 offset:128
	ds_read_b128 v[88:91], v224 offset:160
	ds_read_b128 v[92:95], v224 offset:192
	ds_read_b128 v[96:99], v224 offset:224
	ds_read_b128 v[6:9], v226 offset:49152
	ds_read_b128 v[116:119], v226 offset:57344
	ds_read_b128 v[120:123], v227 offset:49152
	ds_read_b128 v[124:127], v227 offset:57344
	ds_read_b128 v[230:233], v228 offset:49152
	ds_read_b128 v[234:237], v228 offset:57344
	s_waitcnt lgkmcnt(5)
	v_mfma_f32_32x32x16_bf16 v[100:115], v[6:9], v[172:175], v[100:115]
	ds_read_b128 v[6:9], v229 offset:49152
	v_add_f32_e32 v2, 0, v189
	v_add_f32_e32 v2, v191, v2
	v_add_f32_e32 v2, v187, v2
	s_waitcnt lgkmcnt(5)
	v_mfma_f32_32x32x16_bf16 v[84:99], v[116:119], v[172:175], v[84:99]
	ds_read_b128 v[116:119], v229 offset:57344
	v_add_f32_e32 v2, v190, v2
	v_add_f32_e32 v2, v185, v2
	v_add_f32_e32 v2, v188, v2
	s_waitcnt lgkmcnt(5)
	v_mfma_f32_32x32x16_bf16 v[100:115], v[120:123], v[168:171], v[100:115]
	ds_read_b128 v[120:123], v226 offset:49280
	v_add_f32_e32 v2, v184, v2
	v_add_f32_e32 v2, v186, v2
	v_add_f32_e32 v2, v178, v2
	s_waitcnt lgkmcnt(5)
	v_mfma_f32_32x32x16_bf16 v[84:99], v[124:127], v[168:171], v[84:99]
	ds_read_b128 v[124:127], v226 offset:57472
	v_add_f32_e32 v2, v181, v2
	v_add_f32_e32 v2, v177, v2
	v_add_f32_e32 v2, v179, v2
	s_waitcnt lgkmcnt(5)
	v_mfma_f32_32x32x16_bf16 v[100:115], v[230:233], v[164:167], v[100:115]
	ds_read_b128 v[230:233], v227 offset:49280
	v_exp_f32_e32 v1, v142
	v_add_f32_e32 v2, v176, v2
	v_exp_f32_e32 v10, v143
	s_waitcnt lgkmcnt(5)
	v_mfma_f32_32x32x16_bf16 v[84:99], v[234:237], v[164:167], v[84:99]
	ds_read_b128 v[234:237], v227 offset:57472
	v_add_f32_e32 v2, v183, v2
	v_exp_f32_e32 v11, v140
	v_add_f32_e32 v2, v180, v2
	s_waitcnt lgkmcnt(5)
	v_mfma_f32_32x32x16_bf16 v[100:115], v[6:9], v[160:163], v[100:115]
	ds_read_b128 v[6:9], v228 offset:49280
	v_exp_f32_e32 v12, v141
	v_add_f32_e32 v2, v182, v2
	v_exp_f32_e32 v13, v138
	s_waitcnt lgkmcnt(5)
	v_mfma_f32_32x32x16_bf16 v[84:99], v[116:119], v[160:163], v[84:99]
	ds_read_b128 v[116:119], v228 offset:57472
	v_add_f32_e32 v2, v1, v2
	v_exp_f32_e32 v14, v139
	v_add_f32_e32 v2, v10, v2
	s_waitcnt lgkmcnt(5)
	v_mfma_f32_32x32x16_bf16 v[100:115], v[120:123], v[156:159], v[100:115]
	ds_read_b128 v[120:123], v229 offset:49280
	v_exp_f32_e32 v15, v136
	v_add_f32_e32 v2, v11, v2
	v_exp_f32_e32 v80, v137
	s_waitcnt lgkmcnt(5)
	v_mfma_f32_32x32x16_bf16 v[84:99], v[124:127], v[156:159], v[84:99]
	ds_read_b128 v[124:127], v229 offset:57472
	v_add_f32_e32 v2, v12, v2
	v_exp_f32_e32 v81, v134
	v_add_f32_e32 v2, v13, v2
	s_waitcnt lgkmcnt(5)
	v_mfma_f32_32x32x16_bf16 v[100:115], v[230:233], v[152:155], v[100:115]
	v_exp_f32_e32 v82, v135
	v_add_f32_e32 v2, v14, v2
	v_exp_f32_e32 v83, v132
	s_waitcnt lgkmcnt(4)
	v_mfma_f32_32x32x16_bf16 v[84:99], v[234:237], v[152:155], v[84:99]
	v_add_f32_e32 v2, v15, v2
	s_waitcnt lgkmcnt(3)
	v_mfma_f32_32x32x16_bf16 v[100:115], v[6:9], v[148:151], v[100:115]
	s_waitcnt lgkmcnt(2)
	v_mfma_f32_32x32x16_bf16 v[84:99], v[116:119], v[148:151], v[84:99]
	s_waitcnt lgkmcnt(1)
	v_mfma_f32_32x32x16_bf16 v[100:115], v[120:123], v[144:147], v[100:115]
	s_waitcnt lgkmcnt(0)
	v_mfma_f32_32x32x16_bf16 v[84:99], v[124:127], v[144:147], v[84:99]
	s_branch .LBB0_1485
.LBB0_1484:
	v_mov_b32_e32 v14, v0
	v_mov_b32_e32 v15, v0
	v_mov_b32_e32 v1, v0
	v_mov_b32_e32 v2, v0
	v_mov_b32_e32 v3, v0
	v_mov_b32_e32 v4, v0
	v_mov_b32_e32 v5, v0
	v_mov_b32_e32 v6, v0
	v_mov_b32_e32 v7, v0
	v_mov_b32_e32 v8, v0
	v_mov_b32_e32 v9, v0
	v_mov_b32_e32 v10, v0
	v_mov_b32_e32 v11, v0
	v_mov_b32_e32 v12, v0
	v_mov_b32_e32 v13, v0
	v_mov_b64_e32 v[98:99], v[14:15]
	s_waitcnt vmcnt(1)
	v_mov_b64_e32 v[114:115], v[14:15]
	v_mov_b64_e32 v[96:97], v[12:13]
	v_mov_b64_e32 v[94:95], v[10:11]
	v_mov_b64_e32 v[92:93], v[8:9]
	v_mov_b64_e32 v[90:91], v[6:7]
	v_mov_b64_e32 v[88:89], v[4:5]
	v_mov_b64_e32 v[86:87], v[2:3]
	v_mov_b64_e32 v[84:85], v[0:1]
	v_mov_b64_e32 v[112:113], v[12:13]
	v_mov_b64_e32 v[110:111], v[10:11]
	v_mov_b64_e32 v[108:109], v[8:9]
	v_mov_b64_e32 v[106:107], v[6:7]
	v_mov_b64_e32 v[104:105], v[4:5]
	v_mov_b64_e32 v[102:103], v[2:3]
	v_mov_b64_e32 v[100:101], v[0:1]
	v_add_f32_e32 v2, 0, v189
	v_add_f32_e32 v2, v191, v2
	v_add_f32_e32 v2, v187, v2
	v_add_f32_e32 v2, v190, v2
	v_add_f32_e32 v2, v185, v2
	v_add_f32_e32 v2, v188, v2
	v_add_f32_e32 v2, v184, v2
	v_add_f32_e32 v2, v186, v2
	v_add_f32_e32 v2, v178, v2
	v_add_f32_e32 v2, v181, v2
	v_add_f32_e32 v2, v177, v2
	v_add_f32_e32 v2, v179, v2
	v_exp_f32_e32 v1, v142
	v_add_f32_e32 v2, v176, v2
	v_exp_f32_e32 v10, v143
	v_add_f32_e32 v2, v183, v2
	v_exp_f32_e32 v11, v140
	v_add_f32_e32 v2, v180, v2
	v_exp_f32_e32 v12, v141
	v_add_f32_e32 v2, v182, v2
	v_exp_f32_e32 v13, v138
	v_add_f32_e32 v2, v1, v2
	v_exp_f32_e32 v14, v139
	v_add_f32_e32 v2, v10, v2
	v_exp_f32_e32 v15, v136
	v_add_f32_e32 v2, v11, v2
	v_exp_f32_e32 v80, v137
	v_add_f32_e32 v2, v12, v2
	v_exp_f32_e32 v81, v134
	v_add_f32_e32 v2, v13, v2
	v_exp_f32_e32 v82, v135
	v_add_f32_e32 v2, v14, v2
	v_exp_f32_e32 v83, v132
	v_add_f32_e32 v2, v15, v2
.LBB0_1485:
	s_waitcnt vmcnt(0)
	v_exp_f32_e32 v116, v133
	v_add_f32_e32 v2, v80, v2
	v_exp_f32_e32 v117, v130
	v_add_f32_e32 v2, v81, v2
	v_exp_f32_e32 v118, v131
	v_add_f32_e32 v2, v82, v2
	v_exp_f32_e32 v119, v128
	v_add_f32_e32 v2, v83, v2
	v_exp_f32_e32 v120, v129
	v_add_f32_e32 v2, v116, v2
	v_add_f32_e32 v2, v117, v2
	v_add_f32_e32 v2, v118, v2
	v_add_f32_e32 v2, v119, v2
	v_add_f32_e32 v230, v120, v2
	v_mov_b32_e32 v231, v230
	v_cvt_pk_bf16_f32 v2, v189, v191
	v_cvt_pk_bf16_f32 v3, v187, v190
	v_cvt_pk_bf16_f32 v4, v185, v188
	v_cvt_pk_bf16_f32 v5, v184, v186
	v_cvt_pk_bf16_f32 v6, v178, v181
	v_cvt_pk_bf16_f32 v7, v177, v179
	v_cvt_pk_bf16_f32 v8, v176, v183
	v_cvt_pk_bf16_f32 v9, v180, v182
	v_cvt_pk_bf16_f32 v10, v1, v10
	v_cvt_pk_bf16_f32 v11, v11, v12
	v_cvt_pk_bf16_f32 v12, v13, v14
	v_cvt_pk_bf16_f32 v13, v15, v80
	v_cvt_pk_bf16_f32 v80, v81, v82
	v_cvt_pk_bf16_f32 v81, v83, v116
	v_cvt_pk_bf16_f32 v82, v117, v118
	v_cvt_pk_bf16_f32 v83, v119, v120
	s_nop 1
	v_permlane32_swap_b32_e32 v230, v231
	v_permlane32_swap_b32_e32 v2, v4
	v_permlane32_swap_b32_e32 v3, v5
	v_permlane32_swap_b32_e32 v6, v8
	v_permlane32_swap_b32_e32 v7, v9
	v_permlane32_swap_b32_e32 v10, v12
	v_permlane32_swap_b32_e32 v11, v13
	v_permlane32_swap_b32_e32 v80, v82
	v_permlane32_swap_b32_e32 v81, v83
	v_add_u32_e32 v233, s39, v199
	v_add_u32_e32 v1, 1, v233
	v_ashrrev_i32_e32 v117, 31, v1
	v_mad_u64_u32 v[14:15], s[6:7], v1, s83, 0
	v_add_u32_e32 v1, 33, v233
	v_mov_b32_e32 v116, v15
	v_mad_u64_u32 v[118:119], s[6:7], v1, s83, 0
	v_mad_u64_u32 v[116:117], s[6:7], v117, s83, v[116:117]
	v_ashrrev_i32_e32 v121, 31, v1
	v_mov_b32_e32 v120, v119
	v_mov_b32_e32 v15, v116
	v_mad_u64_u32 v[120:121], s[6:7], v121, s83, v[120:121]
	v_lshlrev_b64 v[14:15], 1, v[14:15]
	v_mov_b32_e32 v119, v120
	v_lshl_add_u64 v[116:117], v[200:201], 0, v[14:15]
	v_lshlrev_b64 v[118:119], 1, v[118:119]
	v_lshl_add_u64 v[14:15], v[202:203], 0, v[14:15]
	v_lshl_add_u64 v[120:121], v[200:201], 0, v[118:119]
	global_load_dwordx4 v[176:179], v[116:117], off
	global_load_dwordx4 v[180:183], v[120:121], off
	v_lshl_add_u64 v[116:117], v[202:203], 0, v[118:119]
	global_load_dwordx4 v[184:187], v[14:15], off
	global_load_dwordx4 v[188:191], v[116:117], off
	s_and_b64 vcc, exec, s[4:5]
	s_cbranch_vccnz .LBB0_1487
	ds_read_b64_tr_b16 v[116:117], v216 offset:0
	ds_read_b64_tr_b16 v[118:119], v216 offset:0x800
	ds_read_b64_tr_b16 v[120:121], v216 offset:0x1000
	ds_read_b64_tr_b16 v[122:123], v216 offset:0x1800
	ds_read_b64_tr_b16 v[124:125], v216 offset:0x2000
	ds_read_b64_tr_b16 v[126:127], v216 offset:0x2800
	ds_read_b64_tr_b16 v[128:129], v216 offset:0x3000
	ds_read_b64_tr_b16 v[130:131], v216 offset:0x3800
	s_waitcnt lgkmcnt(0)
	s_nop 0
	v_mfma_f32_32x32x16_bf16 v[48:63], v[2:5], v[116:119], v[48:63]
	ds_read_b64_tr_b16 v[116:117], v216 offset:0x200
	ds_read_b64_tr_b16 v[118:119], v216 offset:0xa00
	v_mfma_f32_32x32x16_bf16 v[48:63], v[6:9], v[120:123], v[48:63]
	ds_read_b64_tr_b16 v[120:121], v216 offset:0x1200
	ds_read_b64_tr_b16 v[122:123], v216 offset:0x1a00
	v_mfma_f32_32x32x16_bf16 v[48:63], v[10:13], v[124:127], v[48:63]
	ds_read_b64_tr_b16 v[124:125], v216 offset:0x2200
	ds_read_b64_tr_b16 v[126:127], v216 offset:0x2a00
	v_mfma_f32_32x32x16_bf16 v[48:63], v[80:83], v[128:131], v[48:63]
	ds_read_b64_tr_b16 v[128:129], v216 offset:0x3200
	ds_read_b64_tr_b16 v[130:131], v216 offset:0x3a00
	s_waitcnt lgkmcnt(0)
	v_mfma_f32_32x32x16_bf16 v[64:79], v[2:5], v[116:119], v[64:79]
	ds_read_b64_tr_b16 v[116:117], v216 offset:0x400
	ds_read_b64_tr_b16 v[118:119], v216 offset:0xc00
	v_mfma_f32_32x32x16_bf16 v[64:79], v[6:9], v[120:123], v[64:79]
	ds_read_b64_tr_b16 v[120:121], v216 offset:0x1400
	ds_read_b64_tr_b16 v[122:123], v216 offset:0x1c00
	v_mfma_f32_32x32x16_bf16 v[64:79], v[10:13], v[124:127], v[64:79]
	ds_read_b64_tr_b16 v[124:125], v216 offset:0x2400
	ds_read_b64_tr_b16 v[126:127], v216 offset:0x2c00
	v_mfma_f32_32x32x16_bf16 v[64:79], v[80:83], v[128:131], v[64:79]
	ds_read_b64_tr_b16 v[128:129], v216 offset:0x3400
	ds_read_b64_tr_b16 v[130:131], v216 offset:0x3c00
	s_waitcnt lgkmcnt(0)
	v_mfma_f32_32x32x16_bf16 v[32:47], v[2:5], v[116:119], v[32:47]
	ds_read_b64_tr_b16 v[116:117], v216 offset:0x600
	ds_read_b64_tr_b16 v[118:119], v216 offset:0xe00
	v_mfma_f32_32x32x16_bf16 v[32:47], v[6:9], v[120:123], v[32:47]
	ds_read_b64_tr_b16 v[120:121], v216 offset:0x1600
	ds_read_b64_tr_b16 v[122:123], v216 offset:0x1e00
	v_mfma_f32_32x32x16_bf16 v[32:47], v[10:13], v[124:127], v[32:47]
	ds_read_b64_tr_b16 v[124:125], v216 offset:0x2600
	ds_read_b64_tr_b16 v[126:127], v216 offset:0x2e00
	v_mfma_f32_32x32x16_bf16 v[32:47], v[80:83], v[128:131], v[32:47]
	ds_read_b64_tr_b16 v[128:129], v216 offset:0x3600
	ds_read_b64_tr_b16 v[130:131], v216 offset:0x3e00
	s_waitcnt lgkmcnt(0)
	v_mfma_f32_32x32x16_bf16 v[16:31], v[2:5], v[116:119], v[16:31]
	v_mfma_f32_32x32x16_bf16 v[16:31], v[6:9], v[120:123], v[16:31]
	v_mfma_f32_32x32x16_bf16 v[16:31], v[10:13], v[124:127], v[16:31]
	v_mfma_f32_32x32x16_bf16 v[16:31], v[80:83], v[128:131], v[16:31]

.LBB0_1493:
	v_cndmask_b32_e64 v234, v1, v192, s[6:7]
	v_mul_f32_e32 v192, 0xbe0293ee, v234
	v_fmamk_f32 v1, v100, 0x3e0293ee, v192
	v_fmamk_f32 v2, v101, 0x3e0293ee, v192
	v_fmamk_f32 v3, v102, 0x3e0293ee, v192
	v_fmamk_f32 v4, v103, 0x3e0293ee, v192
	v_fmamk_f32 v5, v104, 0x3e0293ee, v192
	v_fmamk_f32 v6, v105, 0x3e0293ee, v192
	v_fmamk_f32 v7, v106, 0x3e0293ee, v192
	v_fmamk_f32 v8, v107, 0x3e0293ee, v192
	v_fmamk_f32 v9, v108, 0x3e0293ee, v192
	v_fmamk_f32 v10, v109, 0x3e0293ee, v192
	v_fmamk_f32 v11, v110, 0x3e0293ee, v192
	v_fmamk_f32 v12, v111, 0x3e0293ee, v192
	v_fmamk_f32 v13, v112, 0x3e0293ee, v192
	v_fmamk_f32 v14, v113, 0x3e0293ee, v192
	v_fmamk_f32 v15, v114, 0x3e0293ee, v192
	v_fmamk_f32 v112, v115, 0x3e0293ee, v192
	v_fmamk_f32 v100, v84, 0x3e0293ee, v192
	v_fmamk_f32 v101, v85, 0x3e0293ee, v192
	v_fmamk_f32 v102, v86, 0x3e0293ee, v192
	v_fmamk_f32 v103, v87, 0x3e0293ee, v192
	v_fmamk_f32 v104, v88, 0x3e0293ee, v192
	v_fmamk_f32 v105, v89, 0x3e0293ee, v192
	v_fmamk_f32 v106, v90, 0x3e0293ee, v192
	v_fmamk_f32 v107, v91, 0x3e0293ee, v192
	v_fmamk_f32 v108, v92, 0x3e0293ee, v192
	v_fmamk_f32 v109, v93, 0x3e0293ee, v192
	v_fmamk_f32 v110, v94, 0x3e0293ee, v192
	v_fmamk_f32 v111, v95, 0x3e0293ee, v192
	v_exp_f32_e32 v80, v1
	v_exp_f32_e32 v81, v2
	v_exp_f32_e32 v82, v3
	v_exp_f32_e32 v83, v4
	v_exp_f32_e32 v84, v5
	v_exp_f32_e32 v85, v6
	v_exp_f32_e32 v86, v7
	v_exp_f32_e32 v87, v8
	v_exp_f32_e32 v88, v9
	v_exp_f32_e32 v89, v10
	v_exp_f32_e32 v90, v11
	v_exp_f32_e32 v91, v12
	v_exp_f32_e32 v92, v13
	v_exp_f32_e32 v93, v14
	v_exp_f32_e32 v94, v15
	v_exp_f32_e32 v95, v112
	v_fmamk_f32 v193, v96, 0x3e0293ee, v192
	v_fmamk_f32 v194, v97, 0x3e0293ee, v192
	v_fmamk_f32 v195, v98, 0x3e0293ee, v192
	v_fmac_f32_e32 v192, 0x3e0293ee, v99
	s_waitcnt lgkmcnt(0)
	s_barrier
	s_and_b64 vcc, exec, s[4:5]
	s_cbranch_vccnz .LBB0_1495
	ds_read_b128 v[128:131], v224 offset:256
	ds_read_b128 v[132:135], v224 offset:288
	ds_read_b128 v[136:139], v224 offset:320
	ds_read_b128 v[140:143], v224 offset:352
	ds_read_b128 v[112:115], v224 offset:384
	ds_read_b128 v[116:119], v224 offset:416
	ds_read_b128 v[120:123], v224 offset:448
	ds_read_b128 v[124:127], v224 offset:480
	ds_read_b128 v[236:239], v226 offset:32768
	ds_read_b128 v[240:243], v226 offset:40960
	ds_read_b128 v[244:247], v227 offset:32768
	ds_read_b128 v[248:251], v227 offset:40960
	s_waitcnt lgkmcnt(3)
	v_mfma_f32_32x32x16_bf16 v[128:143], v[236:239], v[172:175], v[128:143]
	ds_read_b128 v[236:239], v228 offset:32768
	v_add_f32_e32 v1, 0, v80
	v_add_f32_e32 v1, v81, v1
	v_add_f32_e32 v1, v82, v1
	v_add_f32_e32 v1, v83, v1
	s_waitcnt lgkmcnt(3)
	v_mfma_f32_32x32x16_bf16 v[112:127], v[240:243], v[172:175], v[112:127]
	ds_read_b128 v[240:243], v228 offset:40960
	v_add_f32_e32 v1, v84, v1
	v_add_f32_e32 v1, v85, v1
	v_add_f32_e32 v1, v86, v1
	v_add_f32_e32 v1, v87, v1
	s_waitcnt lgkmcnt(3)
	v_mfma_f32_32x32x16_bf16 v[128:143], v[244:247], v[168:171], v[128:143]
	ds_read_b128 v[244:247], v229 offset:32768
	v_add_f32_e32 v1, v88, v1
	v_add_f32_e32 v1, v89, v1
	v_add_f32_e32 v1, v90, v1
	v_add_f32_e32 v1, v91, v1
	s_waitcnt lgkmcnt(3)
	v_mfma_f32_32x32x16_bf16 v[112:127], v[248:251], v[168:171], v[112:127]
	ds_read_b128 v[248:251], v229 offset:40960
	v_exp_f32_e32 v96, v100
	v_add_f32_e32 v1, v92, v1
	v_exp_f32_e32 v97, v101
	v_add_f32_e32 v1, v93, v1
	s_waitcnt lgkmcnt(3)
	v_mfma_f32_32x32x16_bf16 v[128:143], v[236:239], v[164:167], v[128:143]
	ds_read_b128 v[236:239], v226 offset:32896
	v_exp_f32_e32 v98, v102
	v_add_f32_e32 v1, v94, v1
	v_exp_f32_e32 v99, v103
	v_add_f32_e32 v1, v95, v1
	s_waitcnt lgkmcnt(3)
	v_mfma_f32_32x32x16_bf16 v[112:127], v[240:243], v[164:167], v[112:127]
	ds_read_b128 v[240:243], v226 offset:41088
	v_exp_f32_e32 v100, v104
	v_add_f32_e32 v1, v96, v1
	v_exp_f32_e32 v101, v105
	v_add_f32_e32 v1, v97, v1
	s_waitcnt lgkmcnt(3)
	v_mfma_f32_32x32x16_bf16 v[128:143], v[244:247], v[160:163], v[128:143]
	ds_read_b128 v[244:247], v227 offset:32896
	v_exp_f32_e32 v102, v106
	v_add_f32_e32 v1, v98, v1
	v_exp_f32_e32 v103, v107
	v_add_f32_e32 v1, v99, v1
	s_waitcnt lgkmcnt(3)
	v_mfma_f32_32x32x16_bf16 v[112:127], v[248:251], v[160:163], v[112:127]
	ds_read_b128 v[248:251], v227 offset:41088
	v_exp_f32_e32 v104, v108
	v_add_f32_e32 v1, v100, v1
	v_exp_f32_e32 v105, v109
	v_add_f32_e32 v1, v101, v1
	s_waitcnt lgkmcnt(3)
	v_mfma_f32_32x32x16_bf16 v[128:143], v[236:239], v[156:159], v[128:143]
	ds_read_b128 v[236:239], v228 offset:32896
	v_exp_f32_e32 v106, v110
	v_add_f32_e32 v1, v102, v1
	v_exp_f32_e32 v107, v111
	v_add_f32_e32 v1, v103, v1
	s_waitcnt lgkmcnt(3)
	v_mfma_f32_32x32x16_bf16 v[112:127], v[240:243], v[156:159], v[112:127]
	ds_read_b128 v[240:243], v228 offset:41088
	v_exp_f32_e32 v108, v193
	v_add_f32_e32 v1, v104, v1
	v_exp_f32_e32 v109, v194
	v_add_f32_e32 v1, v105, v1
	s_waitcnt lgkmcnt(3)
	v_mfma_f32_32x32x16_bf16 v[128:143], v[244:247], v[152:155], v[128:143]
	ds_read_b128 v[244:247], v229 offset:32896
	v_exp_f32_e32 v110, v195
	v_add_f32_e32 v1, v106, v1
	v_exp_f32_e32 v111, v192
	v_add_f32_e32 v1, v107, v1
	s_waitcnt lgkmcnt(3)
	v_mfma_f32_32x32x16_bf16 v[112:127], v[248:251], v[152:155], v[112:127]
	ds_read_b128 v[248:251], v229 offset:41088
	v_add_f32_e32 v1, v108, v1
	v_add_f32_e32 v1, v109, v1
	v_add_f32_e32 v1, v110, v1
	v_add_f32_e32 v1, v111, v1
	s_waitcnt lgkmcnt(3)
	v_mfma_f32_32x32x16_bf16 v[128:143], v[236:239], v[148:151], v[128:143]
	v_mov_b32_e32 v14, v1
	v_cvt_pk_bf16_f32 v2, v80, v81
	v_cvt_pk_bf16_f32 v3, v82, v83
	v_cvt_pk_bf16_f32 v4, v84, v85
	s_waitcnt lgkmcnt(2)
	v_mfma_f32_32x32x16_bf16 v[112:127], v[240:243], v[148:151], v[112:127]
	v_cvt_pk_bf16_f32 v5, v86, v87
	v_cvt_pk_bf16_f32 v6, v88, v89
	v_cvt_pk_bf16_f32 v7, v90, v91
	v_cvt_pk_bf16_f32 v8, v92, v93
	s_waitcnt lgkmcnt(1)
	v_mfma_f32_32x32x16_bf16 v[128:143], v[244:247], v[144:147], v[128:143]
	v_cvt_pk_bf16_f32 v9, v94, v95
	v_cvt_pk_bf16_f32 v10, v96, v97
	v_cvt_pk_bf16_f32 v11, v98, v99
	v_cvt_pk_bf16_f32 v12, v100, v101
	s_waitcnt lgkmcnt(0)
	v_mfma_f32_32x32x16_bf16 v[112:127], v[248:251], v[144:147], v[112:127]
	v_cvt_pk_bf16_f32 v13, v102, v103
	v_cvt_pk_bf16_f32 v192, v104, v105
	v_cvt_pk_bf16_f32 v193, v106, v107
	v_cvt_pk_bf16_f32 v194, v108, v109
	s_branch .LBB0_1496
.LBB0_1495:
	v_mov_b32_e32 v14, v0
	v_mov_b32_e32 v15, v0
	v_mov_b32_e32 v1, v0
	v_mov_b32_e32 v2, v0
	v_mov_b32_e32 v3, v0
	v_mov_b32_e32 v4, v0
	v_mov_b32_e32 v5, v0
	v_mov_b32_e32 v6, v0
	v_mov_b32_e32 v7, v0
	v_mov_b32_e32 v8, v0
	v_mov_b32_e32 v9, v0
	v_mov_b32_e32 v10, v0
	v_mov_b32_e32 v11, v0
	v_mov_b32_e32 v12, v0
	v_mov_b32_e32 v13, v0
	v_mov_b64_e32 v[126:127], v[14:15]
	v_mov_b64_e32 v[142:143], v[14:15]
	v_mov_b64_e32 v[124:125], v[12:13]
	v_mov_b64_e32 v[122:123], v[10:11]
	v_mov_b64_e32 v[120:121], v[8:9]
	v_mov_b64_e32 v[118:119], v[6:7]
	v_mov_b64_e32 v[116:117], v[4:5]
	v_mov_b64_e32 v[114:115], v[2:3]
	v_mov_b64_e32 v[112:113], v[0:1]
	v_mov_b64_e32 v[140:141], v[12:13]
	v_mov_b64_e32 v[138:139], v[10:11]
	v_mov_b64_e32 v[136:137], v[8:9]
	v_mov_b64_e32 v[134:135], v[6:7]
	v_mov_b64_e32 v[132:133], v[4:5]
	v_mov_b64_e32 v[130:131], v[2:3]
	v_mov_b64_e32 v[128:129], v[0:1]
	v_add_f32_e32 v1, 0, v80
	v_add_f32_e32 v1, v81, v1
	v_add_f32_e32 v1, v82, v1
	v_add_f32_e32 v1, v83, v1
	v_add_f32_e32 v1, v84, v1
	v_add_f32_e32 v1, v85, v1
	v_add_f32_e32 v1, v86, v1
	v_add_f32_e32 v1, v87, v1
	v_add_f32_e32 v1, v88, v1
	v_add_f32_e32 v1, v89, v1
	v_add_f32_e32 v1, v90, v1
	v_add_f32_e32 v1, v91, v1
	v_exp_f32_e32 v96, v100
	v_add_f32_e32 v1, v92, v1
	v_exp_f32_e32 v97, v101
	v_add_f32_e32 v1, v93, v1
	v_exp_f32_e32 v98, v102
	v_add_f32_e32 v1, v94, v1
	v_exp_f32_e32 v99, v103
	v_add_f32_e32 v1, v95, v1
	v_exp_f32_e32 v100, v104
	v_add_f32_e32 v1, v96, v1
	v_exp_f32_e32 v101, v105
	v_add_f32_e32 v1, v97, v1
	v_exp_f32_e32 v102, v106
	v_add_f32_e32 v1, v98, v1
	v_exp_f32_e32 v103, v107
	v_add_f32_e32 v1, v99, v1
	v_exp_f32_e32 v104, v108
	v_add_f32_e32 v1, v100, v1
	v_exp_f32_e32 v105, v109
	v_add_f32_e32 v1, v101, v1
	v_exp_f32_e32 v106, v110
	v_add_f32_e32 v1, v102, v1
	v_exp_f32_e32 v107, v111
	v_add_f32_e32 v1, v103, v1
	v_exp_f32_e32 v108, v193
	v_add_f32_e32 v1, v104, v1
	v_exp_f32_e32 v109, v194
	v_add_f32_e32 v1, v105, v1
	v_exp_f32_e32 v110, v195
	v_add_f32_e32 v1, v106, v1
	v_exp_f32_e32 v111, v192
	v_add_f32_e32 v1, v107, v1
	v_add_f32_e32 v1, v108, v1
	v_add_f32_e32 v1, v109, v1
	v_add_f32_e32 v1, v110, v1
	v_add_f32_e32 v1, v111, v1
	v_mov_b32_e32 v14, v1
	v_cvt_pk_bf16_f32 v2, v80, v81
	v_cvt_pk_bf16_f32 v3, v82, v83
	v_cvt_pk_bf16_f32 v4, v84, v85
	v_cvt_pk_bf16_f32 v5, v86, v87
	v_cvt_pk_bf16_f32 v6, v88, v89
	v_cvt_pk_bf16_f32 v7, v90, v91
	v_cvt_pk_bf16_f32 v8, v92, v93
	v_cvt_pk_bf16_f32 v9, v94, v95
	v_cvt_pk_bf16_f32 v10, v96, v97
	v_cvt_pk_bf16_f32 v11, v98, v99
	v_cvt_pk_bf16_f32 v12, v100, v101
	v_cvt_pk_bf16_f32 v13, v102, v103
	v_cvt_pk_bf16_f32 v192, v104, v105
	v_cvt_pk_bf16_f32 v193, v106, v107
	v_cvt_pk_bf16_f32 v194, v108, v109
.LBB0_1496:
	v_cvt_pk_bf16_f32 v195, v110, v111
	s_nop 1
	v_permlane32_swap_b32_e32 v1, v14
	v_permlane32_swap_b32_e32 v2, v4
	v_permlane32_swap_b32_e32 v3, v5
	v_permlane32_swap_b32_e32 v6, v8
	v_permlane32_swap_b32_e32 v7, v9
	v_permlane32_swap_b32_e32 v10, v12
	v_permlane32_swap_b32_e32 v11, v13
	v_permlane32_swap_b32_e32 v192, v194
	v_permlane32_swap_b32_e32 v193, v195
	s_add_i32 s34, s38, 1
	s_cmp_lt_i32 s34, s37
	s_cselect_b64 s[6:7], -1, 0
	s_cmp_ge_i32 s34, s37
	s_cbranch_scc1 .LBB0_1505
	v_add_u32_e32 v15, 0x41, v233
	v_mad_u64_u32 v[176:177], s[34:35], v15, s83, 0
	v_ashrrev_i32_e32 v179, 31, v15
	v_mov_b32_e32 v178, v177
	v_mad_u64_u32 v[178:179], s[34:35], v179, s83, v[178:179]
	v_add_u32_e32 v15, 0x61, v233
	v_mov_b32_e32 v177, v178
	v_mad_u64_u32 v[178:179], s[34:35], v15, s83, 0
	v_ashrrev_i32_e32 v181, 31, v15
	v_mov_b32_e32 v180, v179
	v_mad_u64_u32 v[180:181], s[34:35], v181, s83, v[180:181]
	v_mov_b32_e32 v179, v180
	v_lshlrev_b64 v[184:185], 1, v[176:177]
	v_lshlrev_b64 v[186:187], 1, v[178:179]
	v_lshl_add_u64 v[176:177], v[200:201], 0, v[184:185]
	v_lshl_add_u64 v[180:181], v[200:201], 0, v[186:187]
	v_lshl_add_u64 v[184:185], v[202:203], 0, v[184:185]
	v_lshl_add_u64 v[188:189], v[202:203], 0, v[186:187]
	global_load_dwordx4 v[176:179], v[176:177], off
	s_nop 0
	global_load_dwordx4 v[180:183], v[180:181], off
	s_nop 0
	global_load_dwordx4 v[184:187], v[184:185], off
	s_nop 0
	global_load_dwordx4 v[188:191], v[188:189], off
	s_and_b64 vcc, exec, s[4:5]
	s_cbranch_vccz .LBB0_1506

.LBB0_2854:
	v_cndmask_b32_e64 v1, 0, 1, s[20:21]
	v_cmp_ne_u32_e64 s[38:39], 1, v1
	s_andn2_b64 vcc, exec, s[20:21]
	s_cbranch_vccnz .LBB0_2856
	ds_read_b128 v[100:103], v224
	ds_read_b128 v[104:107], v224 offset:32
	ds_read_b128 v[108:111], v224 offset:64
	s_waitcnt vmcnt(3)
	ds_read_b128 v[112:115], v224 offset:96
	ds_read_b128 v[84:87], v224 offset:128
	ds_read_b128 v[88:91], v224 offset:160
	ds_read_b128 v[92:95], v224 offset:192
	ds_read_b128 v[96:99], v224 offset:224
	ds_read_b128 v[6:9], v226 offset:49152
	ds_read_b128 v[116:119], v226 offset:57344
	ds_read_b128 v[120:123], v227 offset:49152
	ds_read_b128 v[124:127], v227 offset:57344
	ds_read_b128 v[230:233], v228 offset:49152
	ds_read_b128 v[234:237], v228 offset:57344
	s_waitcnt lgkmcnt(5)
	v_mfma_f32_32x32x16_bf16 v[100:115], v[6:9], v[172:175], v[100:115]
	ds_read_b128 v[6:9], v229 offset:49152
	v_add_f32_e32 v2, 0, v189
	v_add_f32_e32 v2, v191, v2
	v_add_f32_e32 v2, v187, v2
	s_waitcnt lgkmcnt(5)
	v_mfma_f32_32x32x16_bf16 v[84:99], v[116:119], v[172:175], v[84:99]
	ds_read_b128 v[116:119], v229 offset:57344
	v_add_f32_e32 v2, v190, v2
	v_add_f32_e32 v2, v185, v2
	v_add_f32_e32 v2, v188, v2
	s_waitcnt lgkmcnt(5)
	v_mfma_f32_32x32x16_bf16 v[100:115], v[120:123], v[168:171], v[100:115]
	ds_read_b128 v[120:123], v226 offset:49280
	v_add_f32_e32 v2, v184, v2
	v_add_f32_e32 v2, v186, v2
	v_add_f32_e32 v2, v178, v2
	s_waitcnt lgkmcnt(5)
	v_mfma_f32_32x32x16_bf16 v[84:99], v[124:127], v[168:171], v[84:99]
	ds_read_b128 v[124:127], v226 offset:57472
	v_add_f32_e32 v2, v181, v2
	v_add_f32_e32 v2, v177, v2
	v_add_f32_e32 v2, v179, v2
	s_waitcnt lgkmcnt(5)
	v_mfma_f32_32x32x16_bf16 v[100:115], v[230:233], v[164:167], v[100:115]
	ds_read_b128 v[230:233], v227 offset:49280
	v_exp_f32_e32 v1, v142
	v_add_f32_e32 v2, v176, v2
	v_exp_f32_e32 v10, v143
	s_waitcnt lgkmcnt(5)
	v_mfma_f32_32x32x16_bf16 v[84:99], v[234:237], v[164:167], v[84:99]
	ds_read_b128 v[234:237], v227 offset:57472
	v_add_f32_e32 v2, v183, v2
	v_exp_f32_e32 v11, v140
	v_add_f32_e32 v2, v180, v2
	s_waitcnt lgkmcnt(5)
	v_mfma_f32_32x32x16_bf16 v[100:115], v[6:9], v[160:163], v[100:115]
	ds_read_b128 v[6:9], v228 offset:49280
	v_exp_f32_e32 v12, v141
	v_add_f32_e32 v2, v182, v2
	v_exp_f32_e32 v13, v138
	s_waitcnt lgkmcnt(5)
	v_mfma_f32_32x32x16_bf16 v[84:99], v[116:119], v[160:163], v[84:99]
	ds_read_b128 v[116:119], v228 offset:57472
	v_add_f32_e32 v2, v1, v2
	v_exp_f32_e32 v14, v139
	v_add_f32_e32 v2, v10, v2
	s_waitcnt lgkmcnt(5)
	v_mfma_f32_32x32x16_bf16 v[100:115], v[120:123], v[156:159], v[100:115]
	ds_read_b128 v[120:123], v229 offset:49280
	v_exp_f32_e32 v15, v136
	v_add_f32_e32 v2, v11, v2
	v_exp_f32_e32 v80, v137
	s_waitcnt lgkmcnt(5)
	v_mfma_f32_32x32x16_bf16 v[84:99], v[124:127], v[156:159], v[84:99]
	ds_read_b128 v[124:127], v229 offset:57472
	v_add_f32_e32 v2, v12, v2
	v_exp_f32_e32 v81, v134
	v_add_f32_e32 v2, v13, v2
	s_waitcnt vmcnt(2) lgkmcnt(5)
	v_mfma_f32_32x32x16_bf16 v[100:115], v[230:233], v[152:155], v[100:115]
	v_exp_f32_e32 v82, v135
	v_add_f32_e32 v2, v14, v2
	v_exp_f32_e32 v83, v132
	s_waitcnt lgkmcnt(4)
	v_mfma_f32_32x32x16_bf16 v[84:99], v[234:237], v[152:155], v[84:99]
	v_add_f32_e32 v2, v15, v2
	s_waitcnt vmcnt(1) lgkmcnt(3)
	v_mfma_f32_32x32x16_bf16 v[100:115], v[6:9], v[148:151], v[100:115]
	s_waitcnt lgkmcnt(2)
	v_mfma_f32_32x32x16_bf16 v[84:99], v[116:119], v[148:151], v[84:99]
	s_waitcnt vmcnt(0) lgkmcnt(1)
	v_mfma_f32_32x32x16_bf16 v[100:115], v[120:123], v[144:147], v[100:115]
	s_waitcnt lgkmcnt(0)
	v_mfma_f32_32x32x16_bf16 v[84:99], v[124:127], v[144:147], v[84:99]
	s_branch .LBB0_2857
.LBB0_2856:
	v_mov_b32_e32 v14, v0
	v_mov_b32_e32 v15, v0
	v_mov_b32_e32 v1, v0
	v_mov_b32_e32 v2, v0
	v_mov_b32_e32 v3, v0
	v_mov_b32_e32 v4, v0
	v_mov_b32_e32 v5, v0
	v_mov_b32_e32 v6, v0
	v_mov_b32_e32 v7, v0
	v_mov_b32_e32 v8, v0
	v_mov_b32_e32 v9, v0
	v_mov_b32_e32 v10, v0
	v_mov_b32_e32 v11, v0
	v_mov_b32_e32 v12, v0
	v_mov_b32_e32 v13, v0
	v_mov_b64_e32 v[98:99], v[14:15]
	s_waitcnt vmcnt(3)
	v_mov_b64_e32 v[114:115], v[14:15]
	v_mov_b64_e32 v[96:97], v[12:13]
	v_mov_b64_e32 v[94:95], v[10:11]
	v_mov_b64_e32 v[92:93], v[8:9]
	v_mov_b64_e32 v[90:91], v[6:7]
	v_mov_b64_e32 v[88:89], v[4:5]
	v_mov_b64_e32 v[86:87], v[2:3]
	v_mov_b64_e32 v[84:85], v[0:1]
	v_mov_b64_e32 v[112:113], v[12:13]
	v_mov_b64_e32 v[110:111], v[10:11]
	v_mov_b64_e32 v[108:109], v[8:9]
	v_mov_b64_e32 v[106:107], v[6:7]
	v_mov_b64_e32 v[104:105], v[4:5]
	v_mov_b64_e32 v[102:103], v[2:3]
	v_mov_b64_e32 v[100:101], v[0:1]
	v_add_f32_e32 v2, 0, v189
	v_add_f32_e32 v2, v191, v2
	v_add_f32_e32 v2, v187, v2
	v_add_f32_e32 v2, v190, v2
	v_add_f32_e32 v2, v185, v2
	v_add_f32_e32 v2, v188, v2
	v_add_f32_e32 v2, v184, v2
	v_add_f32_e32 v2, v186, v2
	v_add_f32_e32 v2, v178, v2
	v_add_f32_e32 v2, v181, v2
	v_add_f32_e32 v2, v177, v2
	v_add_f32_e32 v2, v179, v2
	v_exp_f32_e32 v1, v142
	v_add_f32_e32 v2, v176, v2
	v_exp_f32_e32 v10, v143
	v_add_f32_e32 v2, v183, v2
	v_exp_f32_e32 v11, v140
	v_add_f32_e32 v2, v180, v2
	v_exp_f32_e32 v12, v141
	v_add_f32_e32 v2, v182, v2
	v_exp_f32_e32 v13, v138
	v_add_f32_e32 v2, v1, v2
	v_exp_f32_e32 v14, v139
	v_add_f32_e32 v2, v10, v2
	v_exp_f32_e32 v15, v136
	v_add_f32_e32 v2, v11, v2
	v_exp_f32_e32 v80, v137
	v_add_f32_e32 v2, v12, v2
	v_exp_f32_e32 v81, v134
	v_add_f32_e32 v2, v13, v2
	v_exp_f32_e32 v82, v135
	v_add_f32_e32 v2, v14, v2
	v_exp_f32_e32 v83, v132
	v_add_f32_e32 v2, v15, v2
.LBB0_2857:
	s_waitcnt vmcnt(2)
	v_exp_f32_e32 v116, v133
	v_add_f32_e32 v2, v80, v2
	v_exp_f32_e32 v117, v130
	v_add_f32_e32 v2, v81, v2
	v_exp_f32_e32 v118, v131
	v_add_f32_e32 v2, v82, v2
	v_exp_f32_e32 v119, v128
	v_add_f32_e32 v2, v83, v2
	s_waitcnt vmcnt(1)
	v_exp_f32_e32 v120, v129
	v_add_f32_e32 v2, v116, v2
	v_add_f32_e32 v2, v117, v2
	v_add_f32_e32 v2, v118, v2
	v_add_f32_e32 v2, v119, v2
	v_add_f32_e32 v230, v120, v2
	v_mov_b32_e32 v231, v230
	v_cvt_pk_bf16_f32 v2, v189, v191
	v_cvt_pk_bf16_f32 v3, v187, v190
	v_cvt_pk_bf16_f32 v4, v185, v188
	v_cvt_pk_bf16_f32 v5, v184, v186
	v_cvt_pk_bf16_f32 v6, v178, v181
	v_cvt_pk_bf16_f32 v7, v177, v179
	v_cvt_pk_bf16_f32 v8, v176, v183
	v_cvt_pk_bf16_f32 v9, v180, v182
	v_cvt_pk_bf16_f32 v10, v1, v10
	v_cvt_pk_bf16_f32 v11, v11, v12
	v_cvt_pk_bf16_f32 v12, v13, v14
	v_cvt_pk_bf16_f32 v13, v15, v80
	v_cvt_pk_bf16_f32 v80, v81, v82
	v_cvt_pk_bf16_f32 v81, v83, v116
	v_cvt_pk_bf16_f32 v82, v117, v118
	v_cvt_pk_bf16_f32 v83, v119, v120
	s_nop 1
	v_permlane32_swap_b32_e32 v230, v231
	v_permlane32_swap_b32_e32 v2, v4
	v_permlane32_swap_b32_e32 v3, v5
	v_permlane32_swap_b32_e32 v6, v8
	v_permlane32_swap_b32_e32 v7, v9
	v_permlane32_swap_b32_e32 v10, v12
	v_permlane32_swap_b32_e32 v11, v13
	v_permlane32_swap_b32_e32 v80, v82
	v_permlane32_swap_b32_e32 v81, v83
	v_add_u32_e32 v233, s85, v199
	v_add_u32_e32 v1, 1, v233
	v_ashrrev_i32_e32 v117, 31, v1
	v_mad_u64_u32 v[14:15], s[0:1], v1, s81, 0
	v_add_u32_e32 v1, 33, v233
	v_mov_b32_e32 v116, v15
	v_mad_u64_u32 v[118:119], s[0:1], v1, s81, 0
	v_mad_u64_u32 v[116:117], s[0:1], v117, s81, v[116:117]
	v_ashrrev_i32_e32 v121, 31, v1
	v_mov_b32_e32 v120, v119
	v_mov_b32_e32 v15, v116
	v_mad_u64_u32 v[120:121], s[0:1], v121, s81, v[120:121]
	v_lshlrev_b64 v[14:15], 1, v[14:15]
	v_mov_b32_e32 v119, v120
	v_lshl_add_u64 v[116:117], v[200:201], 0, v[14:15]
	v_lshlrev_b64 v[118:119], 1, v[118:119]
	v_lshl_add_u64 v[14:15], v[202:203], 0, v[14:15]
	v_lshl_add_u64 v[120:121], v[200:201], 0, v[118:119]
	global_load_dwordx4 v[176:179], v[116:117], off
	global_load_dwordx4 v[180:183], v[120:121], off
	v_lshl_add_u64 v[116:117], v[202:203], 0, v[118:119]
	global_load_dwordx4 v[184:187], v[14:15], off
	global_load_dwordx4 v[188:191], v[116:117], off
	s_and_b64 vcc, exec, s[38:39]
	s_cbranch_vccnz .LBB0_2859
	ds_read_b64_tr_b16 v[116:117], v216 offset:0
	ds_read_b64_tr_b16 v[118:119], v216 offset:0x800
	ds_read_b64_tr_b16 v[120:121], v216 offset:0x1000
	ds_read_b64_tr_b16 v[122:123], v216 offset:0x1800
	s_waitcnt vmcnt(4)
	ds_read_b64_tr_b16 v[124:125], v216 offset:0x2000
	ds_read_b64_tr_b16 v[126:127], v216 offset:0x2800
	ds_read_b64_tr_b16 v[128:129], v216 offset:0x3000
	ds_read_b64_tr_b16 v[130:131], v216 offset:0x3800
	s_waitcnt lgkmcnt(0)
	v_mfma_f32_32x32x16_bf16 v[48:63], v[2:5], v[116:119], v[48:63]
	ds_read_b64_tr_b16 v[116:117], v216 offset:0x200
	ds_read_b64_tr_b16 v[118:119], v216 offset:0xa00
	v_mfma_f32_32x32x16_bf16 v[48:63], v[6:9], v[120:123], v[48:63]
	ds_read_b64_tr_b16 v[120:121], v216 offset:0x1200
	ds_read_b64_tr_b16 v[122:123], v216 offset:0x1a00
	v_mfma_f32_32x32x16_bf16 v[48:63], v[10:13], v[124:127], v[48:63]
	ds_read_b64_tr_b16 v[124:125], v216 offset:0x2200
	ds_read_b64_tr_b16 v[126:127], v216 offset:0x2a00
	v_mfma_f32_32x32x16_bf16 v[48:63], v[80:83], v[128:131], v[48:63]
	ds_read_b64_tr_b16 v[128:129], v216 offset:0x3200
	ds_read_b64_tr_b16 v[130:131], v216 offset:0x3a00
	s_waitcnt lgkmcnt(0)
	v_mfma_f32_32x32x16_bf16 v[64:79], v[2:5], v[116:119], v[64:79]
	ds_read_b64_tr_b16 v[116:117], v216 offset:0x400
	ds_read_b64_tr_b16 v[118:119], v216 offset:0xc00
	v_mfma_f32_32x32x16_bf16 v[64:79], v[6:9], v[120:123], v[64:79]
	ds_read_b64_tr_b16 v[120:121], v216 offset:0x1400
	ds_read_b64_tr_b16 v[122:123], v216 offset:0x1c00
	v_mfma_f32_32x32x16_bf16 v[64:79], v[10:13], v[124:127], v[64:79]
	ds_read_b64_tr_b16 v[124:125], v216 offset:0x2400
	ds_read_b64_tr_b16 v[126:127], v216 offset:0x2c00
	v_mfma_f32_32x32x16_bf16 v[64:79], v[80:83], v[128:131], v[64:79]
	ds_read_b64_tr_b16 v[128:129], v216 offset:0x3400
	ds_read_b64_tr_b16 v[130:131], v216 offset:0x3c00
	s_waitcnt lgkmcnt(0)
	v_mfma_f32_32x32x16_bf16 v[32:47], v[2:5], v[116:119], v[32:47]
	ds_read_b64_tr_b16 v[116:117], v216 offset:0x600
	ds_read_b64_tr_b16 v[118:119], v216 offset:0xe00
	v_mfma_f32_32x32x16_bf16 v[32:47], v[6:9], v[120:123], v[32:47]
	ds_read_b64_tr_b16 v[120:121], v216 offset:0x1600
	ds_read_b64_tr_b16 v[122:123], v216 offset:0x1e00
	v_mfma_f32_32x32x16_bf16 v[32:47], v[10:13], v[124:127], v[32:47]
	ds_read_b64_tr_b16 v[124:125], v216 offset:0x2600
	ds_read_b64_tr_b16 v[126:127], v216 offset:0x2e00
	v_mfma_f32_32x32x16_bf16 v[32:47], v[80:83], v[128:131], v[32:47]
	ds_read_b64_tr_b16 v[128:129], v216 offset:0x3600
	ds_read_b64_tr_b16 v[130:131], v216 offset:0x3e00
	s_waitcnt lgkmcnt(0)
	v_mfma_f32_32x32x16_bf16 v[16:31], v[2:5], v[116:119], v[16:31]
	v_mfma_f32_32x32x16_bf16 v[16:31], v[6:9], v[120:123], v[16:31]
	v_mfma_f32_32x32x16_bf16 v[16:31], v[10:13], v[124:127], v[16:31]
	v_mfma_f32_32x32x16_bf16 v[16:31], v[80:83], v[128:131], v[16:31]

.LBB0_2865:
	v_cndmask_b32_e64 v234, v1, v192, s[40:41]
	v_mul_f32_e32 v192, 0xbe0293ee, v234
	v_fmamk_f32 v1, v100, 0x3e0293ee, v192
	v_fmamk_f32 v2, v101, 0x3e0293ee, v192
	v_fmamk_f32 v3, v102, 0x3e0293ee, v192
	v_fmamk_f32 v4, v103, 0x3e0293ee, v192
	v_fmamk_f32 v5, v104, 0x3e0293ee, v192
	v_fmamk_f32 v6, v105, 0x3e0293ee, v192
	v_fmamk_f32 v7, v106, 0x3e0293ee, v192
	v_fmamk_f32 v8, v107, 0x3e0293ee, v192
	v_fmamk_f32 v9, v108, 0x3e0293ee, v192
	v_fmamk_f32 v10, v109, 0x3e0293ee, v192
	v_fmamk_f32 v11, v110, 0x3e0293ee, v192
	v_fmamk_f32 v12, v111, 0x3e0293ee, v192
	v_fmamk_f32 v13, v112, 0x3e0293ee, v192
	v_fmamk_f32 v14, v113, 0x3e0293ee, v192
	v_fmamk_f32 v15, v114, 0x3e0293ee, v192
	v_fmamk_f32 v112, v115, 0x3e0293ee, v192
	v_fmamk_f32 v100, v84, 0x3e0293ee, v192
	v_fmamk_f32 v101, v85, 0x3e0293ee, v192
	v_fmamk_f32 v102, v86, 0x3e0293ee, v192
	v_fmamk_f32 v103, v87, 0x3e0293ee, v192
	v_fmamk_f32 v104, v88, 0x3e0293ee, v192
	v_fmamk_f32 v105, v89, 0x3e0293ee, v192
	v_fmamk_f32 v106, v90, 0x3e0293ee, v192
	v_fmamk_f32 v107, v91, 0x3e0293ee, v192
	v_fmamk_f32 v108, v92, 0x3e0293ee, v192
	v_fmamk_f32 v109, v93, 0x3e0293ee, v192
	v_fmamk_f32 v110, v94, 0x3e0293ee, v192
	v_fmamk_f32 v111, v95, 0x3e0293ee, v192
	v_exp_f32_e32 v80, v1
	v_exp_f32_e32 v81, v2
	v_exp_f32_e32 v82, v3
	v_exp_f32_e32 v83, v4
	v_exp_f32_e32 v84, v5
	v_exp_f32_e32 v85, v6
	v_exp_f32_e32 v86, v7
	v_exp_f32_e32 v87, v8
	v_exp_f32_e32 v88, v9
	v_exp_f32_e32 v89, v10
	v_exp_f32_e32 v90, v11
	v_exp_f32_e32 v91, v12
	v_exp_f32_e32 v92, v13
	v_exp_f32_e32 v93, v14
	v_exp_f32_e32 v94, v15
	v_exp_f32_e32 v95, v112
	v_fmamk_f32 v193, v96, 0x3e0293ee, v192
	v_fmamk_f32 v194, v97, 0x3e0293ee, v192
	v_fmamk_f32 v195, v98, 0x3e0293ee, v192
	v_fmac_f32_e32 v192, 0x3e0293ee, v99
	s_waitcnt lgkmcnt(0)
	s_barrier
	s_and_b64 vcc, exec, s[38:39]
	s_cbranch_vccnz .LBB0_2867
	ds_read_b128 v[128:131], v224 offset:256
	ds_read_b128 v[132:135], v224 offset:288
	ds_read_b128 v[136:139], v224 offset:320
	ds_read_b128 v[140:143], v224 offset:352
	ds_read_b128 v[112:115], v224 offset:384
	ds_read_b128 v[116:119], v224 offset:416
	ds_read_b128 v[120:123], v224 offset:448
	ds_read_b128 v[124:127], v224 offset:480
	ds_read_b128 v[236:239], v226 offset:32768
	ds_read_b128 v[240:243], v226 offset:40960
	ds_read_b128 v[244:247], v227 offset:32768
	ds_read_b128 v[248:251], v227 offset:40960
	s_waitcnt lgkmcnt(3)
	v_mfma_f32_32x32x16_bf16 v[128:143], v[236:239], v[172:175], v[128:143]
	ds_read_b128 v[236:239], v228 offset:32768
	v_add_f32_e32 v1, 0, v80
	v_add_f32_e32 v1, v81, v1
	v_add_f32_e32 v1, v82, v1
	v_add_f32_e32 v1, v83, v1
	s_waitcnt lgkmcnt(3)
	v_mfma_f32_32x32x16_bf16 v[112:127], v[240:243], v[172:175], v[112:127]
	ds_read_b128 v[240:243], v228 offset:40960
	v_add_f32_e32 v1, v84, v1
	v_add_f32_e32 v1, v85, v1
	v_add_f32_e32 v1, v86, v1
	v_add_f32_e32 v1, v87, v1
	s_waitcnt lgkmcnt(3)
	v_mfma_f32_32x32x16_bf16 v[128:143], v[244:247], v[168:171], v[128:143]
	ds_read_b128 v[244:247], v229 offset:32768
	v_add_f32_e32 v1, v88, v1
	v_add_f32_e32 v1, v89, v1
	v_add_f32_e32 v1, v90, v1
	v_add_f32_e32 v1, v91, v1
	s_waitcnt lgkmcnt(3)
	v_mfma_f32_32x32x16_bf16 v[112:127], v[248:251], v[168:171], v[112:127]
	ds_read_b128 v[248:251], v229 offset:40960
	v_exp_f32_e32 v96, v100
	v_add_f32_e32 v1, v92, v1
	v_exp_f32_e32 v97, v101
	v_add_f32_e32 v1, v93, v1
	s_waitcnt lgkmcnt(3)
	v_mfma_f32_32x32x16_bf16 v[128:143], v[236:239], v[164:167], v[128:143]
	ds_read_b128 v[236:239], v226 offset:32896
	v_exp_f32_e32 v98, v102
	v_add_f32_e32 v1, v94, v1
	v_exp_f32_e32 v99, v103
	v_add_f32_e32 v1, v95, v1
	s_waitcnt lgkmcnt(3)
	v_mfma_f32_32x32x16_bf16 v[112:127], v[240:243], v[164:167], v[112:127]
	ds_read_b128 v[240:243], v226 offset:41088
	v_exp_f32_e32 v100, v104
	v_add_f32_e32 v1, v96, v1
	v_exp_f32_e32 v101, v105
	v_add_f32_e32 v1, v97, v1
	s_waitcnt lgkmcnt(3)
	v_mfma_f32_32x32x16_bf16 v[128:143], v[244:247], v[160:163], v[128:143]
	ds_read_b128 v[244:247], v227 offset:32896
	v_exp_f32_e32 v102, v106
	v_add_f32_e32 v1, v98, v1
	v_exp_f32_e32 v103, v107
	v_add_f32_e32 v1, v99, v1
	s_waitcnt lgkmcnt(3)
	v_mfma_f32_32x32x16_bf16 v[112:127], v[248:251], v[160:163], v[112:127]
	ds_read_b128 v[248:251], v227 offset:41088
	v_exp_f32_e32 v104, v108
	v_add_f32_e32 v1, v100, v1
	v_exp_f32_e32 v105, v109
	v_add_f32_e32 v1, v101, v1
	s_waitcnt lgkmcnt(3)
	v_mfma_f32_32x32x16_bf16 v[128:143], v[236:239], v[156:159], v[128:143]
	ds_read_b128 v[236:239], v228 offset:32896
	v_exp_f32_e32 v106, v110
	v_add_f32_e32 v1, v102, v1
	v_exp_f32_e32 v107, v111
	v_add_f32_e32 v1, v103, v1
	s_waitcnt lgkmcnt(3)
	v_mfma_f32_32x32x16_bf16 v[112:127], v[240:243], v[156:159], v[112:127]
	ds_read_b128 v[240:243], v228 offset:41088
	v_exp_f32_e32 v108, v193
	v_add_f32_e32 v1, v104, v1
	v_exp_f32_e32 v109, v194
	v_add_f32_e32 v1, v105, v1
	s_waitcnt lgkmcnt(3)
	v_mfma_f32_32x32x16_bf16 v[128:143], v[244:247], v[152:155], v[128:143]
	ds_read_b128 v[244:247], v229 offset:32896
	v_exp_f32_e32 v110, v195
	v_add_f32_e32 v1, v106, v1
	v_exp_f32_e32 v111, v192
	v_add_f32_e32 v1, v107, v1
	s_waitcnt lgkmcnt(3)
	v_mfma_f32_32x32x16_bf16 v[112:127], v[248:251], v[152:155], v[112:127]
	ds_read_b128 v[248:251], v229 offset:41088
	v_add_f32_e32 v1, v108, v1
	v_add_f32_e32 v1, v109, v1
	v_add_f32_e32 v1, v110, v1
	v_add_f32_e32 v1, v111, v1
	s_waitcnt lgkmcnt(3)
	v_mfma_f32_32x32x16_bf16 v[128:143], v[236:239], v[148:151], v[128:143]
	v_mov_b32_e32 v14, v1
	v_cvt_pk_bf16_f32 v2, v80, v81
	v_cvt_pk_bf16_f32 v3, v82, v83
	v_cvt_pk_bf16_f32 v4, v84, v85
	s_waitcnt lgkmcnt(2)
	v_mfma_f32_32x32x16_bf16 v[112:127], v[240:243], v[148:151], v[112:127]
	v_cvt_pk_bf16_f32 v5, v86, v87
	v_cvt_pk_bf16_f32 v6, v88, v89
	v_cvt_pk_bf16_f32 v7, v90, v91
	v_cvt_pk_bf16_f32 v8, v92, v93
	s_waitcnt lgkmcnt(1)
	v_mfma_f32_32x32x16_bf16 v[128:143], v[244:247], v[144:147], v[128:143]
	v_cvt_pk_bf16_f32 v9, v94, v95
	v_cvt_pk_bf16_f32 v10, v96, v97
	v_cvt_pk_bf16_f32 v11, v98, v99
	v_cvt_pk_bf16_f32 v12, v100, v101
	s_waitcnt lgkmcnt(0)
	v_mfma_f32_32x32x16_bf16 v[112:127], v[248:251], v[144:147], v[112:127]
	v_cvt_pk_bf16_f32 v13, v102, v103
	v_cvt_pk_bf16_f32 v192, v104, v105
	v_cvt_pk_bf16_f32 v193, v106, v107
	v_cvt_pk_bf16_f32 v194, v108, v109
	s_branch .LBB0_2868

.LBB0_2868:
	v_cvt_pk_bf16_f32 v195, v110, v111
	s_nop 1
	v_permlane32_swap_b32_e32 v1, v14
	v_permlane32_swap_b32_e32 v2, v4
	v_permlane32_swap_b32_e32 v3, v5
	v_permlane32_swap_b32_e32 v6, v8
	v_permlane32_swap_b32_e32 v7, v9
	v_permlane32_swap_b32_e32 v10, v12
	v_permlane32_swap_b32_e32 v11, v13
	v_permlane32_swap_b32_e32 v192, v194
	v_permlane32_swap_b32_e32 v193, v195
	s_add_i32 s40, s75, 1
	s_cmp_lt_i32 s40, s28
	s_cselect_b64 s[0:1], -1, 0
	s_cmp_ge_i32 s40, s28
	s_cbranch_scc1 .LBB0_2877
	v_add_u32_e32 v15, 0x41, v233
	v_mad_u64_u32 v[176:177], s[40:41], v15, s81, 0
	v_ashrrev_i32_e32 v179, 31, v15
	v_mov_b32_e32 v178, v177
	v_mad_u64_u32 v[178:179], s[40:41], v179, s81, v[178:179]
	v_add_u32_e32 v15, 0x61, v233
	v_mov_b32_e32 v177, v178
	v_mad_u64_u32 v[178:179], s[40:41], v15, s81, 0
	v_ashrrev_i32_e32 v181, 31, v15
	v_mov_b32_e32 v180, v179
	v_mad_u64_u32 v[180:181], s[40:41], v181, s81, v[180:181]
	v_mov_b32_e32 v179, v180
	v_lshlrev_b64 v[184:185], 1, v[176:177]
	v_lshlrev_b64 v[186:187], 1, v[178:179]
	v_lshl_add_u64 v[176:177], v[200:201], 0, v[184:185]
	v_lshl_add_u64 v[180:181], v[200:201], 0, v[186:187]
	v_lshl_add_u64 v[184:185], v[202:203], 0, v[184:185]
	v_lshl_add_u64 v[188:189], v[202:203], 0, v[186:187]
	global_load_dwordx4 v[176:179], v[176:177], off
	s_nop 0
	global_load_dwordx4 v[180:183], v[180:181], off
	s_nop 0
	global_load_dwordx4 v[184:187], v[184:185], off
	s_nop 0
	global_load_dwordx4 v[188:191], v[188:189], off
	s_and_b64 vcc, exec, s[38:39]
	s_cbranch_vccz .LBB0_2878

.LBB0_4559:
	s_waitcnt vmcnt(2)
	v_exp_f32_e32 v116, v133
	v_add_f32_e32 v2, v80, v2
	v_exp_f32_e32 v117, v130
	v_add_f32_e32 v2, v81, v2
	v_exp_f32_e32 v118, v131
	v_add_f32_e32 v2, v82, v2
	v_exp_f32_e32 v119, v128
	v_add_f32_e32 v2, v83, v2
	s_waitcnt vmcnt(1)
	v_exp_f32_e32 v120, v129
	v_add_f32_e32 v2, v116, v2
	v_add_f32_e32 v2, v117, v2
	v_add_f32_e32 v2, v118, v2
	v_add_f32_e32 v2, v119, v2
	v_add_f32_e32 v230, v120, v2
	v_mov_b32_e32 v231, v230
	v_cvt_pk_bf16_f32 v2, v189, v191
	v_cvt_pk_bf16_f32 v3, v187, v190
	v_cvt_pk_bf16_f32 v4, v185, v188
	v_cvt_pk_bf16_f32 v5, v184, v186
	v_cvt_pk_bf16_f32 v6, v178, v181
	v_cvt_pk_bf16_f32 v7, v177, v179
	v_cvt_pk_bf16_f32 v8, v176, v183
	v_cvt_pk_bf16_f32 v9, v180, v182
	v_cvt_pk_bf16_f32 v10, v1, v10
	v_cvt_pk_bf16_f32 v11, v11, v12
	v_cvt_pk_bf16_f32 v12, v13, v14
	v_cvt_pk_bf16_f32 v13, v15, v80
	v_cvt_pk_bf16_f32 v80, v81, v82
	v_cvt_pk_bf16_f32 v81, v83, v116
	v_cvt_pk_bf16_f32 v82, v117, v118
	v_cvt_pk_bf16_f32 v83, v119, v120
	s_nop 1
	v_permlane32_swap_b32_e32 v230, v231
	v_permlane32_swap_b32_e32 v2, v4
	v_permlane32_swap_b32_e32 v3, v5
	v_permlane32_swap_b32_e32 v6, v8
	v_permlane32_swap_b32_e32 v7, v9
	v_permlane32_swap_b32_e32 v10, v12
	v_permlane32_swap_b32_e32 v11, v13
	v_permlane32_swap_b32_e32 v80, v82
	v_permlane32_swap_b32_e32 v81, v83
	v_add_u32_e32 v233, s89, v199
	v_add_u32_e32 v1, 1, v233
	v_ashrrev_i32_e32 v117, 31, v1
	v_mad_u64_u32 v[14:15], s[0:1], v1, s85, 0
	v_add_u32_e32 v1, 33, v233
	v_mov_b32_e32 v116, v15
	v_mad_u64_u32 v[118:119], s[0:1], v1, s85, 0
	v_mad_u64_u32 v[116:117], s[0:1], v117, s85, v[116:117]
	v_ashrrev_i32_e32 v121, 31, v1
	v_mov_b32_e32 v120, v119
	v_mov_b32_e32 v15, v116
	v_mad_u64_u32 v[120:121], s[0:1], v121, s85, v[120:121]
	v_lshlrev_b64 v[14:15], 1, v[14:15]
	v_mov_b32_e32 v119, v120
	v_lshl_add_u64 v[116:117], v[200:201], 0, v[14:15]
	v_lshlrev_b64 v[118:119], 1, v[118:119]
	v_lshl_add_u64 v[14:15], v[202:203], 0, v[14:15]
	v_lshl_add_u64 v[120:121], v[200:201], 0, v[118:119]
	global_load_dwordx4 v[176:179], v[116:117], off
	global_load_dwordx4 v[180:183], v[120:121], off
	v_lshl_add_u64 v[116:117], v[202:203], 0, v[118:119]
	global_load_dwordx4 v[184:187], v[14:15], off
	global_load_dwordx4 v[188:191], v[116:117], off
	s_and_b64 vcc, exec, s[38:39]
	s_cbranch_vccnz .LBB0_4561
	ds_read_b64_tr_b16 v[116:117], v216 offset:0
	ds_read_b64_tr_b16 v[118:119], v216 offset:0x800
	ds_read_b64_tr_b16 v[120:121], v216 offset:0x1000
	ds_read_b64_tr_b16 v[122:123], v216 offset:0x1800
	s_waitcnt vmcnt(4)
	ds_read_b64_tr_b16 v[124:125], v216 offset:0x2000
	ds_read_b64_tr_b16 v[126:127], v216 offset:0x2800
	ds_read_b64_tr_b16 v[128:129], v216 offset:0x3000
	ds_read_b64_tr_b16 v[130:131], v216 offset:0x3800
	s_waitcnt lgkmcnt(0)
	v_mfma_f32_32x32x16_bf16 v[48:63], v[2:5], v[116:119], v[48:63]
	ds_read_b64_tr_b16 v[116:117], v216 offset:0x200
	ds_read_b64_tr_b16 v[118:119], v216 offset:0xa00
	v_mfma_f32_32x32x16_bf16 v[48:63], v[6:9], v[120:123], v[48:63]
	ds_read_b64_tr_b16 v[120:121], v216 offset:0x1200
	ds_read_b64_tr_b16 v[122:123], v216 offset:0x1a00
	v_mfma_f32_32x32x16_bf16 v[48:63], v[10:13], v[124:127], v[48:63]
	ds_read_b64_tr_b16 v[124:125], v216 offset:0x2200
	ds_read_b64_tr_b16 v[126:127], v216 offset:0x2a00
	v_mfma_f32_32x32x16_bf16 v[48:63], v[80:83], v[128:131], v[48:63]
	ds_read_b64_tr_b16 v[128:129], v216 offset:0x3200
	ds_read_b64_tr_b16 v[130:131], v216 offset:0x3a00
	s_waitcnt lgkmcnt(0)
	v_mfma_f32_32x32x16_bf16 v[64:79], v[2:5], v[116:119], v[64:79]
	ds_read_b64_tr_b16 v[116:117], v216 offset:0x400
	ds_read_b64_tr_b16 v[118:119], v216 offset:0xc00
	v_mfma_f32_32x32x16_bf16 v[64:79], v[6:9], v[120:123], v[64:79]
	ds_read_b64_tr_b16 v[120:121], v216 offset:0x1400
	ds_read_b64_tr_b16 v[122:123], v216 offset:0x1c00
	v_mfma_f32_32x32x16_bf16 v[64:79], v[10:13], v[124:127], v[64:79]
	ds_read_b64_tr_b16 v[124:125], v216 offset:0x2400
	ds_read_b64_tr_b16 v[126:127], v216 offset:0x2c00
	v_mfma_f32_32x32x16_bf16 v[64:79], v[80:83], v[128:131], v[64:79]
	ds_read_b64_tr_b16 v[128:129], v216 offset:0x3400
	ds_read_b64_tr_b16 v[130:131], v216 offset:0x3c00
	s_waitcnt lgkmcnt(0)
	v_mfma_f32_32x32x16_bf16 v[32:47], v[2:5], v[116:119], v[32:47]
	ds_read_b64_tr_b16 v[116:117], v216 offset:0x600
	ds_read_b64_tr_b16 v[118:119], v216 offset:0xe00
	v_mfma_f32_32x32x16_bf16 v[32:47], v[6:9], v[120:123], v[32:47]
	ds_read_b64_tr_b16 v[120:121], v216 offset:0x1600
	ds_read_b64_tr_b16 v[122:123], v216 offset:0x1e00
	v_mfma_f32_32x32x16_bf16 v[32:47], v[10:13], v[124:127], v[32:47]
	ds_read_b64_tr_b16 v[124:125], v216 offset:0x2600
	ds_read_b64_tr_b16 v[126:127], v216 offset:0x2e00
	v_mfma_f32_32x32x16_bf16 v[32:47], v[80:83], v[128:131], v[32:47]
	ds_read_b64_tr_b16 v[128:129], v216 offset:0x3600
	ds_read_b64_tr_b16 v[130:131], v216 offset:0x3e00
	s_waitcnt lgkmcnt(0)
	v_mfma_f32_32x32x16_bf16 v[16:31], v[2:5], v[116:119], v[16:31]
	v_mfma_f32_32x32x16_bf16 v[16:31], v[6:9], v[120:123], v[16:31]
	v_mfma_f32_32x32x16_bf16 v[16:31], v[10:13], v[124:127], v[16:31]
	v_mfma_f32_32x32x16_bf16 v[16:31], v[80:83], v[128:131], v[16:31]

.LBB0_4570:
	v_cvt_pk_bf16_f32 v195, v110, v111
	s_nop 1
	v_permlane32_swap_b32_e32 v1, v14
	v_permlane32_swap_b32_e32 v2, v4
	v_permlane32_swap_b32_e32 v3, v5
	v_permlane32_swap_b32_e32 v6, v8
	v_permlane32_swap_b32_e32 v7, v9
	v_permlane32_swap_b32_e32 v10, v12
	v_permlane32_swap_b32_e32 v11, v13
	v_permlane32_swap_b32_e32 v192, v194
	v_permlane32_swap_b32_e32 v193, v195
	s_add_i32 s40, s77, 1
	s_cmp_lt_i32 s40, s28
	s_cselect_b64 s[0:1], -1, 0
	s_cmp_ge_i32 s40, s28
	s_cbranch_scc1 .LBB0_4579
	v_add_u32_e32 v15, 0x41, v233
	v_mad_u64_u32 v[176:177], s[40:41], v15, s85, 0
	v_ashrrev_i32_e32 v179, 31, v15
	v_mov_b32_e32 v178, v177
	v_mad_u64_u32 v[178:179], s[40:41], v179, s85, v[178:179]
	v_add_u32_e32 v15, 0x61, v233
	v_mov_b32_e32 v177, v178
	v_mad_u64_u32 v[178:179], s[40:41], v15, s85, 0
	v_ashrrev_i32_e32 v181, 31, v15
	v_mov_b32_e32 v180, v179
	v_mad_u64_u32 v[180:181], s[40:41], v181, s85, v[180:181]
	v_mov_b32_e32 v179, v180
	v_lshlrev_b64 v[184:185], 1, v[176:177]
	v_lshlrev_b64 v[186:187], 1, v[178:179]
	v_lshl_add_u64 v[176:177], v[200:201], 0, v[184:185]
	v_lshl_add_u64 v[180:181], v[200:201], 0, v[186:187]
	v_lshl_add_u64 v[184:185], v[202:203], 0, v[184:185]
	v_lshl_add_u64 v[188:189], v[202:203], 0, v[186:187]
	global_load_dwordx4 v[176:179], v[176:177], off
	s_nop 0
	global_load_dwordx4 v[180:183], v[180:181], off
	s_nop 0
	global_load_dwordx4 v[184:187], v[184:185], off
	s_nop 0
	global_load_dwordx4 v[188:191], v[188:189], off
	s_and_b64 vcc, exec, s[38:39]
	s_cbranch_vccz .LBB0_4580

.LBB0_5430:
	s_waitcnt vmcnt(2)
	v_exp_f32_e32 v116, v133
	v_add_f32_e32 v2, v80, v2
	v_exp_f32_e32 v117, v130
	v_add_f32_e32 v2, v81, v2
	v_exp_f32_e32 v118, v131
	v_add_f32_e32 v2, v82, v2
	v_exp_f32_e32 v119, v128
	v_add_f32_e32 v2, v83, v2
	s_waitcnt vmcnt(1)
	v_exp_f32_e32 v120, v129
	v_add_f32_e32 v2, v116, v2
	v_add_f32_e32 v2, v117, v2
	v_add_f32_e32 v2, v118, v2
	v_add_f32_e32 v2, v119, v2
	v_add_f32_e32 v230, v120, v2
	v_mov_b32_e32 v231, v230
	v_cvt_pk_bf16_f32 v2, v189, v191
	v_cvt_pk_bf16_f32 v3, v187, v190
	v_cvt_pk_bf16_f32 v4, v185, v188
	v_cvt_pk_bf16_f32 v5, v184, v186
	v_cvt_pk_bf16_f32 v6, v178, v181
	v_cvt_pk_bf16_f32 v7, v177, v179
	v_cvt_pk_bf16_f32 v8, v176, v183
	v_cvt_pk_bf16_f32 v9, v180, v182
	v_cvt_pk_bf16_f32 v10, v1, v10
	v_cvt_pk_bf16_f32 v11, v11, v12
	v_cvt_pk_bf16_f32 v12, v13, v14
	v_cvt_pk_bf16_f32 v13, v15, v80
	v_cvt_pk_bf16_f32 v80, v81, v82
	v_cvt_pk_bf16_f32 v81, v83, v116
	v_cvt_pk_bf16_f32 v82, v117, v118
	v_cvt_pk_bf16_f32 v83, v119, v120
	s_nop 1
	v_permlane32_swap_b32_e32 v230, v231
	v_permlane32_swap_b32_e32 v2, v4
	v_permlane32_swap_b32_e32 v3, v5
	v_permlane32_swap_b32_e32 v6, v8
	v_permlane32_swap_b32_e32 v7, v9
	v_permlane32_swap_b32_e32 v10, v12
	v_permlane32_swap_b32_e32 v11, v13
	v_permlane32_swap_b32_e32 v80, v82
	v_permlane32_swap_b32_e32 v81, v83
	v_add_u32_e32 v233, s87, v199
	v_add_u32_e32 v1, 1, v233
	v_ashrrev_i32_e32 v117, 31, v1
	v_mad_u64_u32 v[14:15], s[0:1], v1, s82, 0
	v_add_u32_e32 v1, 33, v233
	v_mov_b32_e32 v116, v15
	v_mad_u64_u32 v[118:119], s[0:1], v1, s82, 0
	v_mad_u64_u32 v[116:117], s[0:1], v117, s82, v[116:117]
	v_ashrrev_i32_e32 v121, 31, v1
	v_mov_b32_e32 v120, v119
	v_mov_b32_e32 v15, v116
	v_mad_u64_u32 v[120:121], s[0:1], v121, s82, v[120:121]
	v_lshlrev_b64 v[14:15], 1, v[14:15]
	v_mov_b32_e32 v119, v120
	v_lshl_add_u64 v[116:117], v[200:201], 0, v[14:15]
	v_lshlrev_b64 v[118:119], 1, v[118:119]
	v_lshl_add_u64 v[14:15], v[202:203], 0, v[14:15]
	v_lshl_add_u64 v[120:121], v[200:201], 0, v[118:119]
	global_load_dwordx4 v[176:179], v[116:117], off
	global_load_dwordx4 v[180:183], v[120:121], off
	v_lshl_add_u64 v[116:117], v[202:203], 0, v[118:119]
	global_load_dwordx4 v[184:187], v[14:15], off
	global_load_dwordx4 v[188:191], v[116:117], off
	s_and_b64 vcc, exec, s[38:39]
	s_cbranch_vccnz .LBB0_5432
	ds_read_b64_tr_b16 v[116:117], v216 offset:0
	ds_read_b64_tr_b16 v[118:119], v216 offset:0x800
	ds_read_b64_tr_b16 v[120:121], v216 offset:0x1000
	ds_read_b64_tr_b16 v[122:123], v216 offset:0x1800
	s_waitcnt vmcnt(4)
	ds_read_b64_tr_b16 v[124:125], v216 offset:0x2000
	ds_read_b64_tr_b16 v[126:127], v216 offset:0x2800
	ds_read_b64_tr_b16 v[128:129], v216 offset:0x3000
	ds_read_b64_tr_b16 v[130:131], v216 offset:0x3800
	s_waitcnt lgkmcnt(0)
	v_mfma_f32_32x32x16_bf16 v[48:63], v[2:5], v[116:119], v[48:63]
	ds_read_b64_tr_b16 v[116:117], v216 offset:0x200
	ds_read_b64_tr_b16 v[118:119], v216 offset:0xa00
	v_mfma_f32_32x32x16_bf16 v[48:63], v[6:9], v[120:123], v[48:63]
	ds_read_b64_tr_b16 v[120:121], v216 offset:0x1200
	ds_read_b64_tr_b16 v[122:123], v216 offset:0x1a00
	v_mfma_f32_32x32x16_bf16 v[48:63], v[10:13], v[124:127], v[48:63]
	ds_read_b64_tr_b16 v[124:125], v216 offset:0x2200
	ds_read_b64_tr_b16 v[126:127], v216 offset:0x2a00
	v_mfma_f32_32x32x16_bf16 v[48:63], v[80:83], v[128:131], v[48:63]
	ds_read_b64_tr_b16 v[128:129], v216 offset:0x3200
	ds_read_b64_tr_b16 v[130:131], v216 offset:0x3a00
	s_waitcnt lgkmcnt(0)
	v_mfma_f32_32x32x16_bf16 v[64:79], v[2:5], v[116:119], v[64:79]
	ds_read_b64_tr_b16 v[116:117], v216 offset:0x400
	ds_read_b64_tr_b16 v[118:119], v216 offset:0xc00
	v_mfma_f32_32x32x16_bf16 v[64:79], v[6:9], v[120:123], v[64:79]
	ds_read_b64_tr_b16 v[120:121], v216 offset:0x1400
	ds_read_b64_tr_b16 v[122:123], v216 offset:0x1c00
	v_mfma_f32_32x32x16_bf16 v[64:79], v[10:13], v[124:127], v[64:79]
	ds_read_b64_tr_b16 v[124:125], v216 offset:0x2400
	ds_read_b64_tr_b16 v[126:127], v216 offset:0x2c00
	v_mfma_f32_32x32x16_bf16 v[64:79], v[80:83], v[128:131], v[64:79]
	ds_read_b64_tr_b16 v[128:129], v216 offset:0x3400
	ds_read_b64_tr_b16 v[130:131], v216 offset:0x3c00
	s_waitcnt lgkmcnt(0)
	v_mfma_f32_32x32x16_bf16 v[32:47], v[2:5], v[116:119], v[32:47]
	ds_read_b64_tr_b16 v[116:117], v216 offset:0x600
	ds_read_b64_tr_b16 v[118:119], v216 offset:0xe00
	v_mfma_f32_32x32x16_bf16 v[32:47], v[6:9], v[120:123], v[32:47]
	ds_read_b64_tr_b16 v[120:121], v216 offset:0x1600
	ds_read_b64_tr_b16 v[122:123], v216 offset:0x1e00
	v_mfma_f32_32x32x16_bf16 v[32:47], v[10:13], v[124:127], v[32:47]
	ds_read_b64_tr_b16 v[124:125], v216 offset:0x2600
	ds_read_b64_tr_b16 v[126:127], v216 offset:0x2e00
	v_mfma_f32_32x32x16_bf16 v[32:47], v[80:83], v[128:131], v[32:47]
	ds_read_b64_tr_b16 v[128:129], v216 offset:0x3600
	ds_read_b64_tr_b16 v[130:131], v216 offset:0x3e00
	s_waitcnt lgkmcnt(0)
	v_mfma_f32_32x32x16_bf16 v[16:31], v[2:5], v[116:119], v[16:31]
	v_mfma_f32_32x32x16_bf16 v[16:31], v[6:9], v[120:123], v[16:31]
	v_mfma_f32_32x32x16_bf16 v[16:31], v[10:13], v[124:127], v[16:31]
	v_mfma_f32_32x32x16_bf16 v[16:31], v[80:83], v[128:131], v[16:31]

.LBB0_5441:
	v_cvt_pk_bf16_f32 v195, v110, v111
	s_nop 1
	v_permlane32_swap_b32_e32 v1, v14
	v_permlane32_swap_b32_e32 v2, v4
	v_permlane32_swap_b32_e32 v3, v5
	v_permlane32_swap_b32_e32 v6, v8
	v_permlane32_swap_b32_e32 v7, v9
	v_permlane32_swap_b32_e32 v10, v12
	v_permlane32_swap_b32_e32 v11, v13
	v_permlane32_swap_b32_e32 v192, v194
	v_permlane32_swap_b32_e32 v193, v195
	s_add_i32 s40, s75, 1
	s_cmp_lt_i32 s40, s28
	s_cselect_b64 s[0:1], -1, 0
	s_cmp_ge_i32 s40, s28
	s_cbranch_scc1 .LBB0_5450
	v_add_u32_e32 v15, 0x41, v233
	v_mad_u64_u32 v[176:177], s[40:41], v15, s82, 0
	v_ashrrev_i32_e32 v179, 31, v15
	v_mov_b32_e32 v178, v177
	v_mad_u64_u32 v[178:179], s[40:41], v179, s82, v[178:179]
	v_add_u32_e32 v15, 0x61, v233
	v_mov_b32_e32 v177, v178
	v_mad_u64_u32 v[178:179], s[40:41], v15, s82, 0
	v_ashrrev_i32_e32 v181, 31, v15
	v_mov_b32_e32 v180, v179
	v_mad_u64_u32 v[180:181], s[40:41], v181, s82, v[180:181]
	v_mov_b32_e32 v179, v180
	v_lshlrev_b64 v[184:185], 1, v[176:177]
	v_lshlrev_b64 v[186:187], 1, v[178:179]
	v_lshl_add_u64 v[176:177], v[200:201], 0, v[184:185]
	v_lshl_add_u64 v[180:181], v[200:201], 0, v[186:187]
	v_lshl_add_u64 v[184:185], v[202:203], 0, v[184:185]
	v_lshl_add_u64 v[188:189], v[202:203], 0, v[186:187]
	global_load_dwordx4 v[176:179], v[176:177], off
	s_nop 0
	global_load_dwordx4 v[180:183], v[180:181], off
	s_nop 0
	global_load_dwordx4 v[184:187], v[184:185], off
	s_nop 0
	global_load_dwordx4 v[188:191], v[188:189], off
	s_and_b64 vcc, exec, s[38:39]
	s_cbranch_vccz .LBB0_5451

.LBB0_7258:
	s_waitcnt vmcnt(2)
	v_exp_f32_e32 v116, v133
	v_add_f32_e32 v2, v80, v2
	v_exp_f32_e32 v117, v130
	v_add_f32_e32 v2, v81, v2
	v_exp_f32_e32 v118, v131
	v_add_f32_e32 v2, v82, v2
	v_exp_f32_e32 v119, v128
	v_add_f32_e32 v2, v83, v2
	s_waitcnt vmcnt(1)
	v_exp_f32_e32 v120, v129
	v_add_f32_e32 v2, v116, v2
	v_add_f32_e32 v2, v117, v2
	v_add_f32_e32 v2, v118, v2
	v_add_f32_e32 v2, v119, v2
	v_add_f32_e32 v230, v120, v2
	v_mov_b32_e32 v231, v230
	v_cvt_pk_bf16_f32 v2, v189, v191
	v_cvt_pk_bf16_f32 v3, v187, v190
	v_cvt_pk_bf16_f32 v4, v185, v188
	v_cvt_pk_bf16_f32 v5, v184, v186
	v_cvt_pk_bf16_f32 v6, v178, v181
	v_cvt_pk_bf16_f32 v7, v177, v179
	v_cvt_pk_bf16_f32 v8, v176, v183
	v_cvt_pk_bf16_f32 v9, v180, v182
	v_cvt_pk_bf16_f32 v10, v1, v10
	v_cvt_pk_bf16_f32 v11, v11, v12
	v_cvt_pk_bf16_f32 v12, v13, v14
	v_cvt_pk_bf16_f32 v13, v15, v80
	v_cvt_pk_bf16_f32 v80, v81, v82
	v_cvt_pk_bf16_f32 v81, v83, v116
	v_cvt_pk_bf16_f32 v82, v117, v118
	v_cvt_pk_bf16_f32 v83, v119, v120
	s_nop 1
	v_permlane32_swap_b32_e32 v230, v231
	v_permlane32_swap_b32_e32 v2, v4
	v_permlane32_swap_b32_e32 v3, v5
	v_permlane32_swap_b32_e32 v6, v8
	v_permlane32_swap_b32_e32 v7, v9
	v_permlane32_swap_b32_e32 v10, v12
	v_permlane32_swap_b32_e32 v11, v13
	v_permlane32_swap_b32_e32 v80, v82
	v_permlane32_swap_b32_e32 v81, v83
	v_add_u32_e32 v233, s47, v199
	v_add_u32_e32 v1, 1, v233
	v_ashrrev_i32_e32 v117, 31, v1
	v_mad_u64_u32 v[14:15], s[0:1], v1, s93, 0
	v_add_u32_e32 v1, 33, v233
	v_mov_b32_e32 v116, v15
	v_mad_u64_u32 v[118:119], s[0:1], v1, s93, 0
	v_mad_u64_u32 v[116:117], s[0:1], v117, s93, v[116:117]
	v_ashrrev_i32_e32 v121, 31, v1
	v_mov_b32_e32 v120, v119
	v_mov_b32_e32 v15, v116
	v_mad_u64_u32 v[120:121], s[0:1], v121, s93, v[120:121]
	v_lshlrev_b64 v[14:15], 1, v[14:15]
	v_mov_b32_e32 v119, v120
	v_lshl_add_u64 v[116:117], v[200:201], 0, v[14:15]
	v_lshlrev_b64 v[118:119], 1, v[118:119]
	v_lshl_add_u64 v[14:15], v[202:203], 0, v[14:15]
	v_lshl_add_u64 v[120:121], v[200:201], 0, v[118:119]
	global_load_dwordx4 v[176:179], v[116:117], off
	global_load_dwordx4 v[180:183], v[120:121], off
	v_lshl_add_u64 v[116:117], v[202:203], 0, v[118:119]
	global_load_dwordx4 v[184:187], v[14:15], off
	global_load_dwordx4 v[188:191], v[116:117], off
	s_and_b64 vcc, exec, s[38:39]
	s_cbranch_vccnz .LBB0_7260
	ds_read_b64_tr_b16 v[116:117], v216 offset:0
	ds_read_b64_tr_b16 v[118:119], v216 offset:0x800
	ds_read_b64_tr_b16 v[120:121], v216 offset:0x1000
	ds_read_b64_tr_b16 v[122:123], v216 offset:0x1800
	s_waitcnt vmcnt(4)
	ds_read_b64_tr_b16 v[124:125], v216 offset:0x2000
	ds_read_b64_tr_b16 v[126:127], v216 offset:0x2800
	ds_read_b64_tr_b16 v[128:129], v216 offset:0x3000
	ds_read_b64_tr_b16 v[130:131], v216 offset:0x3800
	s_waitcnt lgkmcnt(0)
	v_mfma_f32_32x32x16_bf16 v[48:63], v[2:5], v[116:119], v[48:63]
	ds_read_b64_tr_b16 v[116:117], v216 offset:0x200
	ds_read_b64_tr_b16 v[118:119], v216 offset:0xa00
	v_mfma_f32_32x32x16_bf16 v[48:63], v[6:9], v[120:123], v[48:63]
	ds_read_b64_tr_b16 v[120:121], v216 offset:0x1200
	ds_read_b64_tr_b16 v[122:123], v216 offset:0x1a00
	v_mfma_f32_32x32x16_bf16 v[48:63], v[10:13], v[124:127], v[48:63]
	ds_read_b64_tr_b16 v[124:125], v216 offset:0x2200
	ds_read_b64_tr_b16 v[126:127], v216 offset:0x2a00
	v_mfma_f32_32x32x16_bf16 v[48:63], v[80:83], v[128:131], v[48:63]
	ds_read_b64_tr_b16 v[128:129], v216 offset:0x3200
	ds_read_b64_tr_b16 v[130:131], v216 offset:0x3a00
	s_waitcnt lgkmcnt(0)
	v_mfma_f32_32x32x16_bf16 v[64:79], v[2:5], v[116:119], v[64:79]
	ds_read_b64_tr_b16 v[116:117], v216 offset:0x400
	ds_read_b64_tr_b16 v[118:119], v216 offset:0xc00
	v_mfma_f32_32x32x16_bf16 v[64:79], v[6:9], v[120:123], v[64:79]
	ds_read_b64_tr_b16 v[120:121], v216 offset:0x1400
	ds_read_b64_tr_b16 v[122:123], v216 offset:0x1c00
	v_mfma_f32_32x32x16_bf16 v[64:79], v[10:13], v[124:127], v[64:79]
	ds_read_b64_tr_b16 v[124:125], v216 offset:0x2400
	ds_read_b64_tr_b16 v[126:127], v216 offset:0x2c00
	v_mfma_f32_32x32x16_bf16 v[64:79], v[80:83], v[128:131], v[64:79]
	ds_read_b64_tr_b16 v[128:129], v216 offset:0x3400
	ds_read_b64_tr_b16 v[130:131], v216 offset:0x3c00
	s_waitcnt lgkmcnt(0)
	v_mfma_f32_32x32x16_bf16 v[32:47], v[2:5], v[116:119], v[32:47]
	ds_read_b64_tr_b16 v[116:117], v216 offset:0x600
	ds_read_b64_tr_b16 v[118:119], v216 offset:0xe00
	v_mfma_f32_32x32x16_bf16 v[32:47], v[6:9], v[120:123], v[32:47]
	ds_read_b64_tr_b16 v[120:121], v216 offset:0x1600
	ds_read_b64_tr_b16 v[122:123], v216 offset:0x1e00
	v_mfma_f32_32x32x16_bf16 v[32:47], v[10:13], v[124:127], v[32:47]
	ds_read_b64_tr_b16 v[124:125], v216 offset:0x2600
	ds_read_b64_tr_b16 v[126:127], v216 offset:0x2e00
	v_mfma_f32_32x32x16_bf16 v[32:47], v[80:83], v[128:131], v[32:47]
	ds_read_b64_tr_b16 v[128:129], v216 offset:0x3600
	ds_read_b64_tr_b16 v[130:131], v216 offset:0x3e00
	s_waitcnt lgkmcnt(0)
	v_mfma_f32_32x32x16_bf16 v[16:31], v[2:5], v[116:119], v[16:31]
	v_mfma_f32_32x32x16_bf16 v[16:31], v[6:9], v[120:123], v[16:31]
	v_mfma_f32_32x32x16_bf16 v[16:31], v[10:13], v[124:127], v[16:31]
	v_mfma_f32_32x32x16_bf16 v[16:31], v[80:83], v[128:131], v[16:31]

.LBB0_7269:
	v_cvt_pk_bf16_f32 v195, v110, v111
	s_nop 1
	v_permlane32_swap_b32_e32 v1, v14
	v_permlane32_swap_b32_e32 v2, v4
	v_permlane32_swap_b32_e32 v3, v5
	v_permlane32_swap_b32_e32 v6, v8
	v_permlane32_swap_b32_e32 v7, v9
	v_permlane32_swap_b32_e32 v10, v12
	v_permlane32_swap_b32_e32 v11, v13
	v_permlane32_swap_b32_e32 v192, v194
	v_permlane32_swap_b32_e32 v193, v195
	s_add_i32 s40, s28, 1
	s_cmp_lt_i32 s40, s27
	s_cselect_b64 s[0:1], -1, 0
	s_cmp_ge_i32 s40, s27
	s_cbranch_scc1 .LBB0_7278
	v_add_u32_e32 v15, 0x41, v233
	v_mad_u64_u32 v[176:177], s[40:41], v15, s93, 0
	v_ashrrev_i32_e32 v179, 31, v15
	v_mov_b32_e32 v178, v177
	v_mad_u64_u32 v[178:179], s[40:41], v179, s93, v[178:179]
	v_add_u32_e32 v15, 0x61, v233
	v_mov_b32_e32 v177, v178
	v_mad_u64_u32 v[178:179], s[40:41], v15, s93, 0
	v_ashrrev_i32_e32 v181, 31, v15
	v_mov_b32_e32 v180, v179
	v_mad_u64_u32 v[180:181], s[40:41], v181, s93, v[180:181]
	v_mov_b32_e32 v179, v180
	v_lshlrev_b64 v[184:185], 1, v[176:177]
	v_lshlrev_b64 v[186:187], 1, v[178:179]
	v_lshl_add_u64 v[176:177], v[200:201], 0, v[184:185]
	v_lshl_add_u64 v[180:181], v[200:201], 0, v[186:187]
	v_lshl_add_u64 v[184:185], v[202:203], 0, v[184:185]
	v_lshl_add_u64 v[188:189], v[202:203], 0, v[186:187]
	global_load_dwordx4 v[176:179], v[176:177], off
	s_nop 0
	global_load_dwordx4 v[180:183], v[180:181], off
	s_nop 0
	global_load_dwordx4 v[184:187], v[184:185], off
	s_nop 0
	global_load_dwordx4 v[188:191], v[188:189], off
	s_and_b64 vcc, exec, s[38:39]
	s_cbranch_vccz .LBB0_7279
